# v34: v30 + combined small de-serialisations (XC staging loads merged, XC weight reads early, G2s epilogue load overlap, S5 P2 counted wait, S5 item loads before the LDS barrier, scalar prefetch addres
# speedup vs baseline: 1.0023x; 1.0023x over previous
; #define LAS __attribute__((address_space(3)))
; DEV void s5_phase(LAS char* shm, const bf16_t* Uin, bf16_t* Yout, const char* tab, const float* dskip) {
;     ...
;         const float2 al = AL[g * NP + lane];
;         const float4 dsk = *(const float4*)(dskip + g * GC + 4 * fq);
;         const bf16_t* vvp = VV + (size_t)g * V_G + ((size_t)(wid * 4) * 64 + lane) * 8; asm volatile("" : "+v"(vvp));
;         bf16x8 va[4][4];
; #pragma unroll
;         for (int q = 0; q < 4; ++q)
; #pragma unroll
;             for (int ks = 0; ks < 4; ++ks) va[q][ks] = *(const bf16x8*)(vvp + ((size_t)((8 * q) * 4 + ks) * 64) * 8);
; #pragma unroll
;         for (int nt = 0; nt < 4; ++nt) *(LAS f32x4*)(shm + SL + (16 * nt + fr) * SRS + (16 * wid + 4 * fq) * 4) = sac[nt];
;         __syncthreads();
;         {
;             float hr = 0.f, hi = 0.f, lr[8], li[8];
; #pragma unroll
;             for (int n = 0; n < 8; ++n) {
;                 lr[n] = hr; li[n] = hi;
;                 const float sr = *(const LAS float*)(shm + SL + (8 * wid + n) * SRS + lane * 4), si = *(const LAS float*)(shm + SL + (8 * wid + n) * SRS + (64 + lane) * 4);
;                 const float nr = al.x * hr - al.y * hi + sr, ni = al.x * hi + al.y * hr + si; hr = nr; hi = ni;
;             }
;             *(LAS float*)(shm + TSEG + (wid * 128 + lane) * 4) = hr; *(LAS float*)(shm + TSEG + (wid * 128 + 64 + lane) * 4) = hi;
.LBB0_300:
	s_lshl_b32 s0, s47, 6
	v_or_b32_e32 v0, s0, v173
	v_lshlrev_b32_e32 v0, 3, v0
	global_load_dwordx2 v[134:135], v0, s[4:5]
	s_add_u32 s0, s15, s0
	v_lshlrev_b32_e32 v168, 2, v173
	s_addc_u32 s1, s16, 0
	s_lshl_b32 s7, s7, 1
	v_and_b32_e32 v0, 48, v173
	s_mul_i32 s10, s45, 0x1080
	v_add_u32_e32 v1, s42, v168
	s_add_u32 s7, s25, s7
	v_add_u32_e32 v138, s10, v1
	global_load_dwordx4 v[18:21], v0, s[0:1]
	s_addc_u32 s10, s26, 0
	s_lshl_b32 s0, s45, 2
	s_ashr_i32 s1, s0, 31
	v_lshrrev_b32_e32 v143, 4, v173
	s_lshl_b64 s[0:1], s[0:1], 10
	v_lshlrev_b32_e32 v144, 2, v143
	s_add_u32 s0, s7, s0
	v_or_b32_e32 v22, s6, v144
	s_addc_u32 s1, s10, s1
	v_lshl_add_u32 v0, v22, 2, s42
	v_lshl_add_u64 v[22:23], s[0:1], 0, v[166:167]
	global_load_dwordx4 v[118:121], v[22:23], off
	global_load_dwordx4 v[86:89], v[22:23], off offset:1024
	global_load_dwordx4 v[46:49], v[22:23], off offset:2048
	global_load_dwordx4 v[34:37], v[22:23], off offset:3072
	v_add_co_u32_e32 v24, vcc, s39, v22
	s_lshl_b32 s7, s45, 3
	s_nop 0
	v_addc_co_u32_e32 v25, vcc, 0, v23, vcc
	v_add_co_u32_e32 v26, vcc, s40, v22
	s_or_b32 s0, s7, 1
	s_nop 0
	v_addc_co_u32_e32 v27, vcc, 0, v23, vcc
	v_add_co_u32_e32 v28, vcc, s41, v22
	v_or_b32_e32 v142, 16, v175
	s_nop 0
	v_addc_co_u32_e32 v29, vcc, 0, v23, vcc
	global_load_dwordx4 v[122:125], v[24:25], off
	global_load_dwordx4 v[90:93], v[24:25], off offset:1024
	s_nop 0
	global_load_dwordx4 v[82:85], v[24:25], off offset:2048
	global_load_dwordx4 v[30:33], v[24:25], off offset:3072
	global_load_dwordx4 v[126:129], v[26:27], off
	global_load_dwordx4 v[94:97], v[26:27], off offset:1024
	global_load_dwordx4 v[42:45], v[26:27], off offset:2048
	s_nop 0
	global_load_dwordx4 v[22:25], v[26:27], off offset:3072
	global_load_dwordx4 v[130:133], v[28:29], off
	global_load_dwordx4 v[98:101], v[28:29], off offset:1024
	global_load_dwordx4 v[38:41], v[28:29], off offset:2048
	s_nop 0
	global_load_dwordx4 v[26:29], v[28:29], off offset:3072
	v_add_u32_e32 v139, v0, v171
	s_mul_i32 s1, s0, 0x210
	v_mad_u32_u24 v0, v142, s29, v0
	v_add_u32_e32 v1, s1, v1
	ds_write_b128 v139, v[162:165]
	ds_write_b128 v0, v[158:161]
	ds_write_b128 v0, v[154:157] offset:8448
	ds_write_b128 v0, v[150:153] offset:16896
	s_waitcnt lgkmcnt(0)
	s_barrier
	ds_read2st64_b32 v[138:139], v138 offset1:1
	ds_read2st64_b32 v[140:141], v1 offset1:1
	ds_read2_b32 v[146:147], v1 offset0:132 offset1:196
	v_add_u32_e32 v0, 32, v1
	ds_read2st64_b32 v[148:149], v0 offset0:4 offset1:5
	v_add_u32_e32 v136, 0, v136
	v_add_u32_e32 v136, v136, v168
	v_add_u32_e32 v136, 0x21200, v136
	v_mov_b32_e32 v137, 0
	s_cmp_lt_i32 s45, 1
	s_waitcnt vmcnt(10)
	v_mul_f32_e32 v159, 0, v135
	v_fma_f32 v145, 0, v134, v159
	v_fma_f32 v0, v134, 0, -v159
	s_waitcnt lgkmcnt(0)
	v_add_f32_e32 v157, v145, v139
	v_add_f32_e32 v158, v0, v138
	v_mul_f32_e32 v0, v135, v157
	v_mul_f32_e32 v138, v134, v157
	v_fma_f32 v0, v134, v158, -v0
	v_fmac_f32_e32 v138, v135, v158
	v_add_f32_e32 v156, v140, v0
	v_add_f32_e32 v155, v141, v138
	v_mul_f32_e32 v138, v135, v156
	v_mul_f32_e32 v0, v135, v155
	v_fmac_f32_e32 v138, v134, v155
	v_fma_f32 v0, v134, v156, -v0
	v_add_f32_e32 v153, v147, v138
	v_add_f32_e32 v154, v146, v0
	v_mul_f32_e32 v0, v135, v153
	v_fma_f32 v0, v134, v154, -v0
	v_add_f32_e32 v151, v148, v0
	v_add_u32_e32 v0, 48, v1
	v_mul_f32_e32 v140, v135, v154
	ds_read2st64_b32 v[138:139], v0 offset0:6 offset1:7
	v_fmac_f32_e32 v140, v134, v153
	v_add_f32_e32 v152, v149, v140
	v_mul_f32_e32 v0, v135, v152
	v_fma_f32 v0, v134, v151, -v0
	s_waitcnt lgkmcnt(0)
	v_add_f32_e32 v149, v138, v0
	v_add_u32_e32 v138, 64, v1
	v_mul_f32_e32 v0, v135, v151
	ds_read2st64_b32 v[140:141], v138 offset0:8 offset1:9
	v_fmac_f32_e32 v0, v134, v152
	v_add_f32_e32 v150, v139, v0
	v_mul_f32_e32 v0, v135, v150
	v_fma_f32 v0, v134, v149, -v0
	v_add_u32_e32 v138, 0x50, v1
	s_waitcnt lgkmcnt(0)
	v_add_f32_e32 v147, v140, v0
	v_mul_f32_e32 v0, v135, v149
	ds_read2st64_b32 v[138:139], v138 offset0:10 offset1:11
	v_fmac_f32_e32 v0, v134, v150
	v_add_f32_e32 v148, v141, v0
	v_mul_f32_e32 v0, v135, v148
	v_fma_f32 v0, v134, v147, -v0
	v_add_u32_e32 v1, 0x60, v1
	s_waitcnt lgkmcnt(0)
	v_add_f32_e32 v145, v138, v0
	v_mul_f32_e32 v0, v135, v147
	ds_read2st64_b32 v[140:141], v1 offset0:12 offset1:13
	v_fmac_f32_e32 v0, v134, v148
	v_add_f32_e32 v146, v139, v0
	v_mul_f32_e32 v0, v135, v146
	v_mul_f32_e32 v1, v135, v145
	v_fma_f32 v0, v134, v145, -v0
	v_fmac_f32_e32 v1, v134, v146
	s_waitcnt lgkmcnt(0)
	v_add_f32_e32 v0, v140, v0
	v_add_f32_e32 v1, v141, v1
	ds_write2st64_b32 v136, v0, v1 offset1:1
	v_mov_b32_e32 v136, 0
	s_waitcnt lgkmcnt(0)
	s_barrier
	s_cbranch_scc1 .LBB0_287
	v_mul_f32_e32 v1, v135, v135
	v_add_f32_e32 v0, v134, v134
	v_fma_f32 v1, v134, v134, -v1
	v_mul_f32_e32 v0, v0, v135
	v_add_f32_e32 v136, v1, v1
	v_mul_f32_e32 v136, v0, v136
	v_mul_f32_e32 v0, v0, v0
	v_fma_f32 v0, v1, v1, -v0
	v_add_f32_e32 v1, v0, v0
	v_mul_f32_e32 v138, v136, v1
	v_mul_f32_e32 v1, v136, v136
	v_fma_f32 v140, v0, v0, -v1
	s_cmp_lt_u32 s45, 8
	v_mov_b32_e32 v141, v140
	s_cbranch_scc1 .LBB0_305
	s_add_i32 s7, 0, 0x21200
	v_mov_b32_e32 v136, 0
	s_and_b32 s1, s45, 0x7ffffff8
	v_mov_b32_e32 v139, v138
	v_add_u32_e32 v160, s7, v168
	s_mov_b32 s7, 0
	v_mov_b32_e32 v137, v136

; DEV float siluf_(float x) { return x * __builtin_amdgcn_rcpf(1.f + __expf(-x)); }
; #define LAS __attribute__((address_space(3)))
; DEV uint4 pack8(const float* f) { return make_uint4(pk2(f[0], f[1]), pk2(f[2], f[3]), pk2(f[4], f[5]), pk2(f[6], f[7])); }
; DEV void xc_gates_phase(LAS char* shm, const bf16_t* mi, bf16_t* xc, const bf16_t* WfT, const float* cw, const float* cb, float* gpart  ) {
;     ...
;             for (int ks = 0; ks < 4; ++ks) {
;                 const int cl = 32 * ks + 8 * fq, c = c0 + cl;
;                 float xv[8], t8[8];
;                 { const f32x4 b0 = *(const LAS f32x4*)(shm + CWL + 16384 + c * 4), b1 = *(const LAS f32x4*)(shm + CWL + 16384 + c * 4 + 16);
;                   xv[0] = b0[0]; xv[1] = b0[1]; xv[2] = b0[2]; xv[3] = b0[3]; xv[4] = b1[0]; xv[5] = b1[1]; xv[6] = b1[2]; xv[7] = b1[3]; }
;                 u32x4 raw3;
; #pragma unroll
;                 for (int tap = 0; tap < 4; ++tap) {
;                     const u32x4 rw = *(const LAS u32x4*)(stg + (fr + tap) * SRS_ + cl * 2);
;                     if (tap == 3) raw3 = rw;
;                     unpack8(make_uint4(rw[0], rw[1], rw[2], rw[3]), t8);
;                     const f32x4 w0 = *(const LAS f32x4*)(shm + CWL + tap * 4096 + c * 4), w1 = *(const LAS f32x4*)(shm + CWL + tap * 4096 + c * 4 + 16);
;                     xv[0] += t8[0] * w0[0]; xv[1] += t8[1] * w0[1]; xv[2] += t8[2] * w0[2]; xv[3] += t8[3] * w0[3];
;                     xv[4] += t8[4] * w1[0]; xv[5] += t8[5] * w1[1]; xv[6] += t8[6] * w1[2]; xv[7] += t8[7] * w1[3];
;                 }
; #pragma unroll
;                 for (int e = 0; e < 8; ++e) xv[e] = siluf_(xv[e]);
;                 const uint4 xp = pack8(xv);
;                 *(uint4*)(xc + (size_t)(m0 + fr) * DM + c) = xp;
;                 const u32x4 xpu = (u32x4){xp.x, xp.y, xp.z, xp.w};
;                 const bf16x8 bx = *(const LAS bf16x8*)(shm + (fr & 7) * WRS + c * 2);
;                 const bf16x8 bv = *(const LAS bf16x8*)(shm + WIMG + (fr & 7) * WRS + c * 2);
;                 acc = __builtin_amdgcn_mfma_f32_16x16x32_bf16(*(const bf16x8*)&xpu, bx, acc, 0, 0, 0);
;                 acc = __builtin_amdgcn_mfma_f32_16x16x32_bf16(*(const bf16x8*)&raw3, bv, acc, 0, 0, 0);
;             }
.LBB0_358:
	ds_read_b128 v[90:93], v5 offset:16384
	ds_read_b128 v[94:97], v5 offset:16400
	ds_read_b128 v[98:101], v5
	ds_read_b128 v[102:105], v5 offset:16
	ds_read_b128 v[106:109], v89
	ds_read_b128 v[110:113], v89 offset:528
	ds_read_b128 v[114:117], v5 offset:4096
	ds_read_b128 v[118:121], v5 offset:4112
	ds_read_b128 v[122:125], v5 offset:8192
	ds_read_b128 v[126:129], v5 offset:8208
	ds_read_b128 v[130:133], v89 offset:1056
	ds_read_b128 v[50:53], v89 offset:1584
	ds_read_b128 v[134:137], v5 offset:12288
	ds_read_b128 v[138:141], v5 offset:12304
	s_waitcnt lgkmcnt(9)
	ds_read_b128 v[142:145], v3
	ds_read_b128 v[146:149], v3 offset:16512
	v_lshlrev_b32_e32 v152, 16, v106
	v_and_b32_e32 v153, 0xffff0000, v106
	v_lshlrev_b32_e32 v106, 16, v107
	v_and_b32_e32 v107, 0xffff0000, v107
	v_lshlrev_b32_e32 v162, 16, v108
	v_and_b32_e32 v163, 0xffff0000, v108
	v_lshlrev_b32_e32 v108, 16, v109
	v_and_b32_e32 v109, 0xffff0000, v109
	s_waitcnt lgkmcnt(10)
	v_lshlrev_b32_e32 v154, 16, v110
	v_and_b32_e32 v155, 0xffff0000, v110
	v_lshlrev_b32_e32 v110, 16, v111
	v_and_b32_e32 v111, 0xffff0000, v111
	v_lshlrev_b32_e32 v164, 16, v112
	v_and_b32_e32 v165, 0xffff0000, v112
	v_lshlrev_b32_e32 v112, 16, v113
	v_and_b32_e32 v113, 0xffff0000, v113
	v_pk_fma_f32 v[90:91], v[98:99], v[152:153], v[90:91]
	v_pk_fma_f32 v[92:93], v[100:101], v[106:107], v[92:93]
	v_pk_fma_f32 v[94:95], v[102:103], v[162:163], v[94:95]
	v_pk_fma_f32 v[96:97], v[104:105], v[108:109], v[96:97]
	s_waitcnt lgkmcnt(5)
	v_lshlrev_b32_e32 v156, 16, v130
	v_and_b32_e32 v157, 0xffff0000, v130
	v_lshlrev_b32_e32 v130, 16, v131
	v_and_b32_e32 v131, 0xffff0000, v131
	v_lshlrev_b32_e32 v166, 16, v132
	v_and_b32_e32 v167, 0xffff0000, v132
	v_lshlrev_b32_e32 v132, 16, v133
	v_and_b32_e32 v133, 0xffff0000, v133
	v_pk_fma_f32 v[90:91], v[114:115], v[154:155], v[90:91]
	v_pk_fma_f32 v[92:93], v[116:117], v[110:111], v[92:93]
	v_pk_fma_f32 v[94:95], v[118:119], v[164:165], v[94:95]
	v_pk_fma_f32 v[96:97], v[120:121], v[112:113], v[96:97]
	s_waitcnt lgkmcnt(4)
	v_lshlrev_b32_e32 v158, 16, v50
	v_and_b32_e32 v159, 0xffff0000, v50
	v_lshlrev_b32_e32 v160, 16, v51
	v_and_b32_e32 v161, 0xffff0000, v51
	v_lshlrev_b32_e32 v168, 16, v52
	v_and_b32_e32 v169, 0xffff0000, v52
	v_lshlrev_b32_e32 v170, 16, v53
	v_and_b32_e32 v171, 0xffff0000, v53
	v_pk_fma_f32 v[90:91], v[122:123], v[156:157], v[90:91]
	v_pk_fma_f32 v[92:93], v[124:125], v[130:131], v[92:93]
	v_pk_fma_f32 v[94:95], v[126:127], v[166:167], v[94:95]
	v_pk_fma_f32 v[96:97], v[128:129], v[132:133], v[96:97]
	s_waitcnt lgkmcnt(3)
	v_pk_fma_f32 v[90:91], v[134:135], v[158:159], v[90:91]
	v_pk_fma_f32 v[92:93], v[136:137], v[160:161], v[92:93]
	s_waitcnt lgkmcnt(2)
	v_pk_fma_f32 v[94:95], v[138:139], v[168:169], v[94:95]
	v_pk_fma_f32 v[96:97], v[140:141], v[170:171], v[96:97]
	v_mul_f32_e32 v0, 0xbfb8aa3b, v90
	v_mul_f32_e32 v1, 0xbfb8aa3b, v91
	v_mul_f32_e32 v98, 0xbfb8aa3b, v92
	v_mul_f32_e32 v99, 0xbfb8aa3b, v93
	v_mul_f32_e32 v100, 0xbfb8aa3b, v94
	v_mul_f32_e32 v101, 0xbfb8aa3b, v95
	v_mul_f32_e32 v102, 0xbfb8aa3b, v96
	v_mul_f32_e32 v103, 0xbfb8aa3b, v97
	v_exp_f32_e32 v0, v0
	v_exp_f32_e32 v1, v1
	v_exp_f32_e32 v98, v98
	v_exp_f32_e32 v99, v99
	v_exp_f32_e32 v100, v100
	v_exp_f32_e32 v101, v101
	v_exp_f32_e32 v102, v102
	v_exp_f32_e32 v103, v103
	v_add_f32_e32 v0, 1.0, v0
	v_add_f32_e32 v1, 1.0, v1
	v_add_f32_e32 v104, 1.0, v98
	v_add_f32_e32 v105, 1.0, v99
	v_add_f32_e32 v106, 1.0, v100
	v_add_f32_e32 v107, 1.0, v101
	v_add_f32_e32 v108, 1.0, v102
	v_add_f32_e32 v109, 1.0, v103
	v_rcp_f32_e32 v98, v0
	v_rcp_f32_e32 v99, v1
	v_rcp_f32_e32 v100, v104
	v_rcp_f32_e32 v101, v105
	v_rcp_f32_e32 v102, v106
	v_rcp_f32_e32 v103, v107
	v_rcp_f32_e32 v104, v108
	v_rcp_f32_e32 v105, v109
	v_pk_mul_f32 v[90:91], v[90:91], v[98:99]
	v_pk_mul_f32 v[92:93], v[92:93], v[100:101]
	v_pk_mul_f32 v[94:95], v[94:95], v[102:103]
	v_pk_mul_f32 v[96:97], v[96:97], v[104:105]
	v_cvt_pk_bf16_f32 v90, v90, v91
	v_cvt_pk_bf16_f32 v91, v92, v93
	v_cvt_pk_bf16_f32 v92, v94, v95
	v_cvt_pk_bf16_f32 v93, v96, v97
	s_waitcnt lgkmcnt(1)
	v_mfma_f32_16x16x32_bf16 v[38:41], v[90:93], v[142:145], v[38:41]
	v_lshl_add_u64 v[150:151], v[74:75], 0, s[26:27]
	s_add_u32 s26, s26, 64
	v_add_co_u32_e32 v94, vcc, s31, v150
	s_waitcnt lgkmcnt(0)
	v_mfma_f32_16x16x32_bf16 v[38:41], v[50:53], v[146:149], v[38:41]
	s_addc_u32 s27, s27, 0
	v_add_u32_e32 v89, 64, v89
	v_add_u32_e32 v3, 64, v3
	v_add_u32_e32 v5, 0x80, v5
	v_addc_co_u32_e32 v95, vcc, 0, v151, vcc
	s_cmpk_eq_i32 s26, 0x100
	global_store_dwordx4 v[94:95], v[90:93], off sc1
	s_cbranch_scc0 .LBB0_358
	ds_write_b128 v87, v[18:21] offset:53504
	ds_write_b128 v87, v[26:29] offset:55616
	ds_write_b128 v87, v[34:37] offset:57728
	ds_write_b128 v87, v[42:45] offset:59840
	s_and_saveexec_b64 s[0:1], s[4:5]
	ds_write_b128 v88, v[46:49] offset:53504
	s_or_b64 exec, exec, s[0:1]
	s_and_b64 vcc, exec, s[24:25]
	s_cbranch_vccz .LBB0_373
	v_mov_b32_e32 v28, v2
	v_mov_b32_e32 v29, v2
	v_mov_b64_e32 v[20:21], v[28:29]
	v_mov_b64_e32 v[18:19], v[28:29]
	s_and_saveexec_b64 s[0:1], s[6:7]
	s_cbranch_execz .LBB0_364
	global_load_dwordx4 v[18:21], v[64:65], off offset:768

; DEV float siluf_(float x) { return x * __builtin_amdgcn_rcpf(1.f + __expf(-x)); }
; #define LAS __attribute__((address_space(3)))
; DEV uint4 pack8(const float* f) { return make_uint4(pk2(f[0], f[1]), pk2(f[2], f[3]), pk2(f[4], f[5]), pk2(f[6], f[7])); }
; DEV void xc_gates_phase(LAS char* shm, const bf16_t* mi, bf16_t* xc, const bf16_t* WfT, const float* cw, const float* cb, float* gpart  ) {
;     ...
;             for (int ks = 0; ks < 4; ++ks) {
;                 const int cl = 32 * ks + 8 * fq, c = c0 + cl;
;                 float xv[8], t8[8];
;                 { const f32x4 b0 = *(const LAS f32x4*)(shm + CWL + 16384 + c * 4), b1 = *(const LAS f32x4*)(shm + CWL + 16384 + c * 4 + 16);
;                   xv[0] = b0[0]; xv[1] = b0[1]; xv[2] = b0[2]; xv[3] = b0[3]; xv[4] = b1[0]; xv[5] = b1[1]; xv[6] = b1[2]; xv[7] = b1[3]; }
;                 u32x4 raw3;
; #pragma unroll
;                 for (int tap = 0; tap < 4; ++tap) {
;                     const u32x4 rw = *(const LAS u32x4*)(stg + (fr + tap) * SRS_ + cl * 2);
;                     if (tap == 3) raw3 = rw;
;                     unpack8(make_uint4(rw[0], rw[1], rw[2], rw[3]), t8);
;                     const f32x4 w0 = *(const LAS f32x4*)(shm + CWL + tap * 4096 + c * 4), w1 = *(const LAS f32x4*)(shm + CWL + tap * 4096 + c * 4 + 16);
;                     xv[0] += t8[0] * w0[0]; xv[1] += t8[1] * w0[1]; xv[2] += t8[2] * w0[2]; xv[3] += t8[3] * w0[3];
;                     xv[4] += t8[4] * w1[0]; xv[5] += t8[5] * w1[1]; xv[6] += t8[6] * w1[2]; xv[7] += t8[7] * w1[3];
;                 }
; #pragma unroll
;                 for (int e = 0; e < 8; ++e) xv[e] = siluf_(xv[e]);
;                 const uint4 xp = pack8(xv);
;                 *(uint4*)(xc + (size_t)(m0 + fr) * DM + c) = xp;
;                 const u32x4 xpu = (u32x4){xp.x, xp.y, xp.z, xp.w};
;                 const bf16x8 bx = *(const LAS bf16x8*)(shm + (fr & 7) * WRS + c * 2);
;                 const bf16x8 bv = *(const LAS bf16x8*)(shm + WIMG + (fr & 7) * WRS + c * 2);
;                 acc = __builtin_amdgcn_mfma_f32_16x16x32_bf16(*(const bf16x8*)&xpu, bx, acc, 0, 0, 0);
;                 acc = __builtin_amdgcn_mfma_f32_16x16x32_bf16(*(const bf16x8*)&raw3, bv, acc, 0, 0, 0);
;             }
.LBB0_374:
	ds_read_b128 v[90:93], v74 offset:16384
	ds_read_b128 v[94:97], v74 offset:16400
	ds_read_b128 v[98:101], v74
	ds_read_b128 v[102:105], v74 offset:16
	ds_read_b128 v[106:109], v75
	ds_read_b128 v[110:113], v75 offset:528
	ds_read_b128 v[114:117], v74 offset:4096
	ds_read_b128 v[118:121], v74 offset:4112
	ds_read_b128 v[122:125], v74 offset:8192
	ds_read_b128 v[126:129], v74 offset:8208
	ds_read_b128 v[130:133], v75 offset:1056
	ds_read_b128 v[50:53], v75 offset:1584
	ds_read_b128 v[134:137], v74 offset:12288
	ds_read_b128 v[138:141], v74 offset:12304
	s_waitcnt lgkmcnt(9)
	ds_read_b128 v[142:145], v3
	ds_read_b128 v[146:149], v3 offset:16512
	v_lshlrev_b32_e32 v152, 16, v106
	v_and_b32_e32 v153, 0xffff0000, v106
	v_lshlrev_b32_e32 v106, 16, v107
	v_and_b32_e32 v107, 0xffff0000, v107
	v_lshlrev_b32_e32 v162, 16, v108
	v_and_b32_e32 v163, 0xffff0000, v108
	v_lshlrev_b32_e32 v108, 16, v109
	v_and_b32_e32 v109, 0xffff0000, v109
	s_waitcnt lgkmcnt(10)
	v_lshlrev_b32_e32 v154, 16, v110
	v_and_b32_e32 v155, 0xffff0000, v110
	v_lshlrev_b32_e32 v110, 16, v111
	v_and_b32_e32 v111, 0xffff0000, v111
	v_lshlrev_b32_e32 v164, 16, v112
	v_and_b32_e32 v165, 0xffff0000, v112
	v_lshlrev_b32_e32 v112, 16, v113
	v_and_b32_e32 v113, 0xffff0000, v113
	v_pk_fma_f32 v[90:91], v[98:99], v[152:153], v[90:91]
	v_pk_fma_f32 v[92:93], v[100:101], v[106:107], v[92:93]
	v_pk_fma_f32 v[94:95], v[102:103], v[162:163], v[94:95]
	v_pk_fma_f32 v[96:97], v[104:105], v[108:109], v[96:97]
	s_waitcnt lgkmcnt(5)
	v_lshlrev_b32_e32 v156, 16, v130
	v_and_b32_e32 v157, 0xffff0000, v130
	v_lshlrev_b32_e32 v130, 16, v131
	v_and_b32_e32 v131, 0xffff0000, v131
	v_lshlrev_b32_e32 v166, 16, v132
	v_and_b32_e32 v167, 0xffff0000, v132
	v_lshlrev_b32_e32 v132, 16, v133
	v_and_b32_e32 v133, 0xffff0000, v133
	v_pk_fma_f32 v[90:91], v[114:115], v[154:155], v[90:91]
	v_pk_fma_f32 v[92:93], v[116:117], v[110:111], v[92:93]
	v_pk_fma_f32 v[94:95], v[118:119], v[164:165], v[94:95]
	v_pk_fma_f32 v[96:97], v[120:121], v[112:113], v[96:97]
	s_waitcnt lgkmcnt(4)
	v_lshlrev_b32_e32 v158, 16, v50
	v_and_b32_e32 v159, 0xffff0000, v50
	v_lshlrev_b32_e32 v160, 16, v51
	v_and_b32_e32 v161, 0xffff0000, v51
	v_lshlrev_b32_e32 v168, 16, v52
	v_and_b32_e32 v169, 0xffff0000, v52
	v_lshlrev_b32_e32 v170, 16, v53
	v_and_b32_e32 v171, 0xffff0000, v53
	v_pk_fma_f32 v[90:91], v[122:123], v[156:157], v[90:91]
	v_pk_fma_f32 v[92:93], v[124:125], v[130:131], v[92:93]
	v_pk_fma_f32 v[94:95], v[126:127], v[166:167], v[94:95]
	v_pk_fma_f32 v[96:97], v[128:129], v[132:133], v[96:97]
	s_waitcnt lgkmcnt(3)
	v_pk_fma_f32 v[90:91], v[134:135], v[158:159], v[90:91]
	v_pk_fma_f32 v[92:93], v[136:137], v[160:161], v[92:93]
	s_waitcnt lgkmcnt(2)
	v_pk_fma_f32 v[94:95], v[138:139], v[168:169], v[94:95]
	v_pk_fma_f32 v[96:97], v[140:141], v[170:171], v[96:97]
	v_mul_f32_e32 v0, 0xbfb8aa3b, v90
	v_mul_f32_e32 v1, 0xbfb8aa3b, v91
	v_mul_f32_e32 v89, 0xbfb8aa3b, v92
	v_mul_f32_e32 v98, 0xbfb8aa3b, v93
	v_mul_f32_e32 v99, 0xbfb8aa3b, v94
	v_mul_f32_e32 v100, 0xbfb8aa3b, v95
	v_mul_f32_e32 v101, 0xbfb8aa3b, v96
	v_mul_f32_e32 v102, 0xbfb8aa3b, v97
	v_exp_f32_e32 v0, v0
	v_exp_f32_e32 v1, v1
	v_exp_f32_e32 v89, v89
	v_exp_f32_e32 v98, v98
	v_exp_f32_e32 v99, v99
	v_exp_f32_e32 v100, v100
	v_exp_f32_e32 v101, v101
	v_exp_f32_e32 v102, v102
	v_add_f32_e32 v0, 1.0, v0
	v_add_f32_e32 v1, 1.0, v1
	v_add_f32_e32 v89, 1.0, v89
	v_add_f32_e32 v103, 1.0, v98
	v_add_f32_e32 v104, 1.0, v99
	v_add_f32_e32 v105, 1.0, v100
	v_add_f32_e32 v106, 1.0, v101
	v_add_f32_e32 v107, 1.0, v102
	v_rcp_f32_e32 v98, v0
	v_rcp_f32_e32 v99, v1
	v_rcp_f32_e32 v100, v89
	v_rcp_f32_e32 v101, v103
	v_rcp_f32_e32 v102, v104
	v_rcp_f32_e32 v103, v105
	v_rcp_f32_e32 v104, v106
	v_rcp_f32_e32 v105, v107
	v_pk_mul_f32 v[90:91], v[90:91], v[98:99]
	v_pk_mul_f32 v[92:93], v[92:93], v[100:101]
	v_pk_mul_f32 v[94:95], v[94:95], v[102:103]
	v_pk_mul_f32 v[96:97], v[96:97], v[104:105]
	v_cvt_pk_bf16_f32 v90, v90, v91
	v_cvt_pk_bf16_f32 v91, v92, v93
	v_cvt_pk_bf16_f32 v92, v94, v95
	v_cvt_pk_bf16_f32 v93, v96, v97
	s_waitcnt lgkmcnt(1)
	v_mfma_f32_16x16x32_bf16 v[38:41], v[90:93], v[142:145], v[38:41]
	v_lshl_add_u64 v[150:151], v[4:5], 0, s[24:25]
	s_add_u32 s24, s24, 64
	v_add_co_u32_e32 v94, vcc, s31, v150
	s_waitcnt lgkmcnt(0)
	v_mfma_f32_16x16x32_bf16 v[38:41], v[50:53], v[146:149], v[38:41]
	s_addc_u32 s25, s25, 0
	v_add_u32_e32 v75, 64, v75
	v_add_u32_e32 v3, 64, v3
	v_add_u32_e32 v74, 0x80, v74
	v_addc_co_u32_e32 v95, vcc, 0, v151, vcc
	s_cmpk_lg_i32 s24, 0x100
	global_store_dwordx4 v[94:95], v[90:93], off offset:256 sc1
	s_cbranch_scc1 .LBB0_374
	s_movk_i32 s19, 0x100
	s_mov_b64 s[24:25], 0
	s_and_b64 vcc, exec, s[22:23]
	s_cbranch_vccz .LBB0_343
	s_and_saveexec_b64 s[0:1], s[14:15]
	s_cbranch_execz .LBB0_321
	s_ashr_i32 s19, s18, 31
	v_lshl_add_u64 v[4:5], s[18:19], 0, v[58:59]
	v_lshlrev_b64 v[4:5], 5, v[4:5]
	v_lshl_add_u64 v[4:5], v[54:55], 0, v[4:5]
	global_store_dword v[4:5], v38, off
	global_store_dword v[4:5], v39, off offset:32
	global_store_dword v[4:5], v40, off offset:64
	global_store_dword v[4:5], v41, off offset:96
	s_branch .LBB0_321

; #define MLK_ISSUE(chunk_off_elems, buf) do { const char* kg_ = (const char*)(k + (chunk_off_elems)); _Pragma("unroll") for (int i_ = 0; i_ < 4; ++i_) \
;             __builtin_amdgcn_global_load_lds((const unsigned*)(kg_ + kvoff + (size_t)i_ * 16 * DM * 2), (LAS unsigned*)(shm + (buf) * 32768 + (i_ * 8 + wid) * 1024), 16, 0, 0); } while (0)
; template <int SKIP>
; DEV void mlstm_phase(LAS char* shm, const bf16_t* q, const bf16_t* k, const bf16_t* v, const float* gpart, const float* b_ig, const float* b_fg, bf16_t* hc, const bool pre) {
;     ...
;             if (j + 1 < SEQ / CHUNK) {
;                 const size_t cn = cb + (size_t)CHUNK * DM;
;                 MLK_ISSUE(cn, (j + 1) & 1);
; #pragma unroll
;                 for (int ks = 0; ks < 8; ++ks) qnx[ks] = *(const bf16x8*)(qfb + (size_t)(j + 1) * 16384 + ks * 512);
;                 if (wid < 4) vv = *(const uint4*)(v + cn + (size_t)(tid >> 2) * DM + vs * 32 + (tid & 3) * 8);
;             }
.LBB0_650:
	s_waitcnt lgkmcnt(0)
	s_barrier
	s_and_b64 vcc, exec, s[84:85]
	s_cbranch_vccnz .Lpf0_done
	s_cmpk_eq_i32 s40, 0xff00
	s_cbranch_scc1 .Lpf0_skip
	v_lshl_add_u64 v[0:1], v[168:169], 0, s[74:75]
	s_mov_b64 s[0:1], 0x2032000
	v_lshl_add_u64 v[4:5], v[0:1], 0, s[0:1]
	s_add_i32 s0, s38, 0x8000
	s_and_b32 s0, s0, 0x8000
	s_add_i32 s29, s65, s0
	s_mov_b32 m0, s29
	s_mov_b64 s[0:1], 0x203a000
	global_load_lds_dwordx4 v[4:5], off
	v_lshl_add_u64 v[4:5], v[0:1], 0, s[0:1]
	s_add_i32 m0, s29, 0x2000
	s_mov_b64 s[0:1], 0x2042000
	global_load_lds_dwordx4 v[4:5], off
	v_lshl_add_u64 v[4:5], v[0:1], 0, s[0:1]
	s_add_i32 m0, s29, 0x4000
	s_mov_b64 s[0:1], 0x204a000
	global_load_lds_dwordx4 v[4:5], off
	v_lshl_add_u64 v[0:1], v[0:1], 0, s[0:1]
	s_add_i32 m0, s29, 0x6000
	global_load_lds_dwordx4 v[0:1], off
	s_add_u32 s0, s38, 0xc074000
	s_addc_u32 s1, s39, 0
	v_lshl_add_u64 v[4:5], v[170:171], 0, s[0:1]
	s_add_u32 s0, s0, 0x1000
	s_addc_u32 s1, s1, 0
	global_load_dwordx4 v[98:101], v[4:5], off
	global_load_dwordx4 v[90:93], v[4:5], off offset:1024
	global_load_dwordx4 v[82:85], v[4:5], off offset:2048
	global_load_dwordx4 v[78:81], v[4:5], off offset:3072
	v_lshl_add_u64 v[0:1], v[170:171], 0, s[0:1]
	global_load_dwordx4 v[106:109], v[0:1], off
	global_load_dwordx4 v[102:105], v[0:1], off offset:1024
	global_load_dwordx4 v[94:97], v[0:1], off offset:2048
	global_load_dwordx4 v[86:89], v[0:1], off offset:3072
	s_add_u32 s0, s74, 0xa07a000
	s_addc_u32 s1, s75, 0
	v_lshl_add_u64 v[0:1], v[174:175], 0, s[0:1]
	global_load_dwordx4 v[6:9], v[0:1], off

; #define LAS __attribute__((address_space(3)))
; DEV void s5_phase(LAS char* shm, const bf16_t* Uin, bf16_t* Yout, const char* tab, const float* dskip) {
;     ...
;         const float2 al = AL[g * NP + lane];
;         const float4 dsk = *(const float4*)(dskip + g * GC + 4 * fq);
;         const bf16_t* vvp = VV + (size_t)g * V_G + ((size_t)(wid * 4) * 64 + lane) * 8; asm volatile("" : "+v"(vvp));
;         bf16x8 va[4][4];
; #pragma unroll
;         for (int q = 0; q < 4; ++q)
; #pragma unroll
;             for (int ks = 0; ks < 4; ++ks) va[q][ks] = *(const bf16x8*)(vvp + ((size_t)((8 * q) * 4 + ks) * 64) * 8);
; #pragma unroll
;         for (int nt = 0; nt < 4; ++nt) *(LAS f32x4*)(shm + SL + (16 * nt + fr) * SRS + (16 * wid + 4 * fq) * 4) = sac[nt];
;         __syncthreads();
;         {
;             float hr = 0.f, hi = 0.f, lr[8], li[8];
; #pragma unroll
;             for (int n = 0; n < 8; ++n) {
;                 lr[n] = hr; li[n] = hi;
;                 const float sr = *(const LAS float*)(shm + SL + (8 * wid + n) * SRS + lane * 4), si = *(const LAS float*)(shm + SL + (8 * wid + n) * SRS + (64 + lane) * 4);
;                 const float nr = al.x * hr - al.y * hi + sr, ni = al.x * hi + al.y * hr + si; hr = nr; hi = ni;
;             }
;             *(LAS float*)(shm + TSEG + (wid * 128 + lane) * 4) = hr; *(LAS float*)(shm + TSEG + (wid * 128 + 64 + lane) * 4) = hi;
.LBB0_1155:
	s_lshl_b32 s0, s45, 6
	v_or_b32_e32 v0, s0, v173
	v_lshlrev_b32_e32 v0, 3, v0
	global_load_dwordx2 v[134:135], v0, s[4:5]
	s_add_u32 s0, s21, s0
	v_lshlrev_b32_e32 v168, 2, v173
	s_addc_u32 s1, s22, 0
	s_lshl_b32 s7, s7, 1
	v_and_b32_e32 v0, 48, v173
	s_mul_i32 s10, s43, 0x1080
	v_add_u32_e32 v138, s40, v168
	s_add_u32 s7, s25, s7
	v_add_u32_e32 v139, s10, v138
	global_load_dwordx4 v[18:21], v0, s[0:1]
	s_addc_u32 s10, s26, 0
	s_lshl_b32 s0, s43, 2
	v_lshrrev_b32_e32 v143, 4, v173
	s_ashr_i32 s1, s0, 31
	v_lshlrev_b32_e32 v144, 2, v143
	s_lshl_b64 s[0:1], s[0:1], 10
	v_or_b32_e32 v1, s6, v144
	s_add_u32 s0, s7, s0
	v_or_b32_e32 v142, 16, v175
	v_lshl_add_u32 v0, v1, 2, s40
	s_addc_u32 s1, s10, s1
	v_add_u32_e32 v140, v0, v171
	v_mad_u32_u24 v141, v142, s29, v0
	v_lshl_add_u64 v[0:1], s[0:1], 0, v[166:167]
	global_load_dwordx4 v[118:121], v[0:1], off
	global_load_dwordx4 v[86:89], v[0:1], off offset:1024
	global_load_dwordx4 v[46:49], v[0:1], off offset:2048
	global_load_dwordx4 v[34:37], v[0:1], off offset:3072
	v_add_co_u32_e32 v22, vcc, s37, v0
	s_lshl_b32 s7, s43, 3
	s_nop 0
	v_addc_co_u32_e32 v23, vcc, 0, v1, vcc
	v_add_co_u32_e32 v24, vcc, s38, v0
	s_or_b32 s0, s7, 1
	s_nop 0
	v_addc_co_u32_e32 v25, vcc, 0, v1, vcc
	v_add_co_u32_e32 v0, vcc, s39, v0
	s_mul_i32 s1, s0, 0x210
	s_nop 0
	v_addc_co_u32_e32 v1, vcc, 0, v1, vcc
	global_load_dwordx4 v[122:125], v[22:23], off
	global_load_dwordx4 v[90:93], v[22:23], off offset:1024
	s_nop 0
	global_load_dwordx4 v[82:85], v[22:23], off offset:2048
	global_load_dwordx4 v[30:33], v[22:23], off offset:3072
	global_load_dwordx4 v[126:129], v[24:25], off
	global_load_dwordx4 v[94:97], v[24:25], off offset:1024
	global_load_dwordx4 v[42:45], v[24:25], off offset:2048
	s_nop 0
	global_load_dwordx4 v[22:25], v[24:25], off offset:3072
	s_nop 0
	global_load_dwordx4 v[130:133], v[0:1], off
	global_load_dwordx4 v[98:101], v[0:1], off offset:1024
	global_load_dwordx4 v[38:41], v[0:1], off offset:2048
	global_load_dwordx4 v[26:29], v[0:1], off offset:3072
	v_add_u32_e32 v166, s1, v138
	ds_write_b128 v140, v[162:165]
	ds_write_b128 v141, v[158:161]
	ds_write_b128 v141, v[154:157] offset:8448
	ds_write_b128 v141, v[150:153] offset:16896
	s_waitcnt lgkmcnt(0)
	s_barrier
	ds_read2st64_b32 v[0:1], v139 offset1:1
	ds_read2st64_b32 v[138:139], v166 offset1:1
	ds_read2_b32 v[140:141], v166 offset0:132 offset1:196
	v_add_u32_e32 v145, 32, v166
	ds_read2st64_b32 v[146:147], v145 offset0:4 offset1:5
	v_add_u32_e32 v136, 0, v136
	v_add_u32_e32 v136, v136, v168
	v_add_u32_e32 v136, 0x21200, v136
	v_mov_b32_e32 v137, 0
	s_cmp_lt_i32 s43, 1
	s_waitcnt vmcnt(10)
	v_mul_f32_e32 v159, 0, v135
	v_fma_f32 v148, 0, v134, v159
	v_fma_f32 v145, v134, 0, -v159
	s_waitcnt lgkmcnt(0)
	v_add_f32_e32 v157, v148, v1
	v_add_f32_e32 v158, v145, v0
	v_mul_f32_e32 v0, v135, v157
	v_mul_f32_e32 v1, v134, v157
	v_fma_f32 v0, v134, v158, -v0
	v_fmac_f32_e32 v1, v135, v158
	v_add_f32_e32 v156, v138, v0
	v_add_f32_e32 v155, v139, v1
	v_mul_f32_e32 v1, v135, v156
	v_mul_f32_e32 v0, v135, v155
	v_fmac_f32_e32 v1, v134, v155
	v_fma_f32 v0, v134, v156, -v0
	v_add_f32_e32 v153, v141, v1
	v_add_f32_e32 v154, v140, v0
	v_mul_f32_e32 v0, v135, v153
	v_fma_f32 v0, v134, v154, -v0
	v_add_f32_e32 v151, v146, v0
	v_add_u32_e32 v0, 48, v166
	v_mul_f32_e32 v138, v135, v154
	ds_read2st64_b32 v[0:1], v0 offset0:6 offset1:7
	v_fmac_f32_e32 v138, v134, v153
	v_add_f32_e32 v152, v147, v138
	v_mul_f32_e32 v138, v135, v152
	v_fma_f32 v138, v134, v151, -v138
	s_waitcnt lgkmcnt(0)
	v_add_f32_e32 v149, v0, v138
	v_add_u32_e32 v138, 64, v166
	v_mul_f32_e32 v0, v135, v151
	ds_read2st64_b32 v[138:139], v138 offset0:8 offset1:9
	v_fmac_f32_e32 v0, v134, v152
	v_add_f32_e32 v150, v1, v0
	v_mul_f32_e32 v0, v135, v150
	v_fma_f32 v0, v134, v149, -v0
	s_waitcnt lgkmcnt(0)
	v_add_f32_e32 v147, v138, v0
	v_add_u32_e32 v0, 0x50, v166
	v_mul_f32_e32 v138, v135, v149
	ds_read2st64_b32 v[0:1], v0 offset0:10 offset1:11
	v_fmac_f32_e32 v138, v134, v150
	v_add_f32_e32 v148, v139, v138
	v_mul_f32_e32 v138, v135, v148
	v_fma_f32 v138, v134, v147, -v138
	s_waitcnt lgkmcnt(0)
	v_add_f32_e32 v145, v0, v138
	v_add_u32_e32 v138, 0x60, v166
	v_mul_f32_e32 v0, v135, v147
	ds_read2st64_b32 v[138:139], v138 offset0:12 offset1:13
	v_fmac_f32_e32 v0, v134, v148
	v_add_f32_e32 v146, v1, v0
	v_mul_f32_e32 v0, v135, v146
	v_mul_f32_e32 v1, v135, v145
	v_fma_f32 v0, v134, v145, -v0
	v_fmac_f32_e32 v1, v134, v146
	s_waitcnt lgkmcnt(0)
	v_add_f32_e32 v0, v138, v0
	v_add_f32_e32 v1, v139, v1
	ds_write2st64_b32 v136, v0, v1 offset1:1
	v_mov_b32_e32 v136, 0
	s_waitcnt lgkmcnt(0)
	s_barrier
	s_cbranch_scc1 .LBB0_1142
	v_mul_f32_e32 v1, v135, v135
	v_add_f32_e32 v0, v134, v134
	v_fma_f32 v1, v134, v134, -v1
	v_mul_f32_e32 v0, v0, v135
	v_add_f32_e32 v136, v1, v1
	v_mul_f32_e32 v136, v0, v136
	v_mul_f32_e32 v0, v0, v0
	v_fma_f32 v0, v1, v1, -v0
	v_add_f32_e32 v1, v0, v0
	v_mul_f32_e32 v138, v136, v1
	v_mul_f32_e32 v1, v136, v136
	v_fma_f32 v140, v0, v0, -v1
	s_cmp_lt_u32 s43, 8
	v_mov_b32_e32 v141, v140
	s_cbranch_scc1 .LBB0_1160
	s_add_i32 s7, 0, 0x21200
	v_mov_b32_e32 v136, 0
	s_and_b32 s1, s43, 0x7ffffff8
	v_mov_b32_e32 v139, v138
	v_add_u32_e32 v160, s7, v168
	s_mov_b32 s7, 0
	v_mov_b32_e32 v137, v136

; DEV float siluf_(float x) { return x * __builtin_amdgcn_rcpf(1.f + __expf(-x)); }
; #define LAS __attribute__((address_space(3)))
; DEV uint4 pack8(const float* f) { return make_uint4(pk2(f[0], f[1]), pk2(f[2], f[3]), pk2(f[4], f[5]), pk2(f[6], f[7])); }
; DEV void xc_gates_phase(LAS char* shm, const bf16_t* mi, bf16_t* xc, const bf16_t* WfT, const float* cw, const float* cb, float* gpart  ) {
;     ...
;             for (int ks = 0; ks < 4; ++ks) {
;                 const int cl = 32 * ks + 8 * fq, c = c0 + cl;
;                 float xv[8], t8[8];
;                 { const f32x4 b0 = *(const LAS f32x4*)(shm + CWL + 16384 + c * 4), b1 = *(const LAS f32x4*)(shm + CWL + 16384 + c * 4 + 16);
;                   xv[0] = b0[0]; xv[1] = b0[1]; xv[2] = b0[2]; xv[3] = b0[3]; xv[4] = b1[0]; xv[5] = b1[1]; xv[6] = b1[2]; xv[7] = b1[3]; }
;                 u32x4 raw3;
; #pragma unroll
;                 for (int tap = 0; tap < 4; ++tap) {
;                     const u32x4 rw = *(const LAS u32x4*)(stg + (fr + tap) * SRS_ + cl * 2);
;                     if (tap == 3) raw3 = rw;
;                     unpack8(make_uint4(rw[0], rw[1], rw[2], rw[3]), t8);
;                     const f32x4 w0 = *(const LAS f32x4*)(shm + CWL + tap * 4096 + c * 4), w1 = *(const LAS f32x4*)(shm + CWL + tap * 4096 + c * 4 + 16);
;                     xv[0] += t8[0] * w0[0]; xv[1] += t8[1] * w0[1]; xv[2] += t8[2] * w0[2]; xv[3] += t8[3] * w0[3];
;                     xv[4] += t8[4] * w1[0]; xv[5] += t8[5] * w1[1]; xv[6] += t8[6] * w1[2]; xv[7] += t8[7] * w1[3];
;                 }
; #pragma unroll
;                 for (int e = 0; e < 8; ++e) xv[e] = siluf_(xv[e]);
;                 const uint4 xp = pack8(xv);
;                 *(uint4*)(xc + (size_t)(m0 + fr) * DM + c) = xp;
;                 const u32x4 xpu = (u32x4){xp.x, xp.y, xp.z, xp.w};
;                 const bf16x8 bx = *(const LAS bf16x8*)(shm + (fr & 7) * WRS + c * 2);
;                 const bf16x8 bv = *(const LAS bf16x8*)(shm + WIMG + (fr & 7) * WRS + c * 2);
;                 acc = __builtin_amdgcn_mfma_f32_16x16x32_bf16(*(const bf16x8*)&xpu, bx, acc, 0, 0, 0);
;                 acc = __builtin_amdgcn_mfma_f32_16x16x32_bf16(*(const bf16x8*)&raw3, bv, acc, 0, 0, 0);
;             }
.LBB0_1213:
	ds_read_b128 v[90:93], v5 offset:16384
	ds_read_b128 v[94:97], v5 offset:16400
	ds_read_b128 v[98:101], v5
	ds_read_b128 v[102:105], v5 offset:16
	ds_read_b128 v[106:109], v89
	ds_read_b128 v[110:113], v89 offset:528
	ds_read_b128 v[114:117], v5 offset:4096
	ds_read_b128 v[118:121], v5 offset:4112
	ds_read_b128 v[122:125], v5 offset:8192
	ds_read_b128 v[126:129], v5 offset:8208
	ds_read_b128 v[130:133], v89 offset:1056
	ds_read_b128 v[50:53], v89 offset:1584
	ds_read_b128 v[134:137], v5 offset:12288
	ds_read_b128 v[138:141], v5 offset:12304
	s_waitcnt lgkmcnt(9)
	ds_read_b128 v[142:145], v3
	ds_read_b128 v[146:149], v3 offset:16512
	v_lshlrev_b32_e32 v150, 16, v106
	v_and_b32_e32 v151, 0xffff0000, v106
	v_lshlrev_b32_e32 v106, 16, v107
	v_and_b32_e32 v107, 0xffff0000, v107
	v_lshlrev_b32_e32 v160, 16, v108
	v_and_b32_e32 v161, 0xffff0000, v108
	v_lshlrev_b32_e32 v108, 16, v109
	v_and_b32_e32 v109, 0xffff0000, v109
	s_waitcnt lgkmcnt(10)
	v_lshlrev_b32_e32 v152, 16, v110
	v_and_b32_e32 v153, 0xffff0000, v110
	v_lshlrev_b32_e32 v110, 16, v111
	v_and_b32_e32 v111, 0xffff0000, v111
	v_lshlrev_b32_e32 v162, 16, v112
	v_and_b32_e32 v163, 0xffff0000, v112
	v_lshlrev_b32_e32 v112, 16, v113
	v_and_b32_e32 v113, 0xffff0000, v113
	v_pk_fma_f32 v[90:91], v[98:99], v[150:151], v[90:91]
	v_pk_fma_f32 v[92:93], v[100:101], v[106:107], v[92:93]
	v_pk_fma_f32 v[94:95], v[102:103], v[160:161], v[94:95]
	v_pk_fma_f32 v[96:97], v[104:105], v[108:109], v[96:97]
	s_waitcnt lgkmcnt(5)
	v_lshlrev_b32_e32 v154, 16, v130
	v_and_b32_e32 v155, 0xffff0000, v130
	v_lshlrev_b32_e32 v130, 16, v131
	v_and_b32_e32 v131, 0xffff0000, v131
	v_lshlrev_b32_e32 v164, 16, v132
	v_and_b32_e32 v165, 0xffff0000, v132
	v_lshlrev_b32_e32 v132, 16, v133
	v_and_b32_e32 v133, 0xffff0000, v133
	v_pk_fma_f32 v[90:91], v[114:115], v[152:153], v[90:91]
	v_pk_fma_f32 v[92:93], v[116:117], v[110:111], v[92:93]
	v_pk_fma_f32 v[94:95], v[118:119], v[162:163], v[94:95]
	v_pk_fma_f32 v[96:97], v[120:121], v[112:113], v[96:97]
	s_waitcnt lgkmcnt(4)
	v_lshlrev_b32_e32 v156, 16, v50
	v_and_b32_e32 v157, 0xffff0000, v50
	v_lshlrev_b32_e32 v158, 16, v51
	v_and_b32_e32 v159, 0xffff0000, v51
	v_lshlrev_b32_e32 v166, 16, v52
	v_and_b32_e32 v167, 0xffff0000, v52
	v_lshlrev_b32_e32 v168, 16, v53
	v_and_b32_e32 v169, 0xffff0000, v53
	v_pk_fma_f32 v[90:91], v[122:123], v[154:155], v[90:91]
	v_pk_fma_f32 v[92:93], v[124:125], v[130:131], v[92:93]
	v_pk_fma_f32 v[94:95], v[126:127], v[164:165], v[94:95]
	v_pk_fma_f32 v[96:97], v[128:129], v[132:133], v[96:97]
	s_waitcnt lgkmcnt(3)
	v_pk_fma_f32 v[90:91], v[134:135], v[156:157], v[90:91]
	v_pk_fma_f32 v[92:93], v[136:137], v[158:159], v[92:93]
	s_waitcnt lgkmcnt(2)
	v_pk_fma_f32 v[94:95], v[138:139], v[166:167], v[94:95]
	v_pk_fma_f32 v[96:97], v[140:141], v[168:169], v[96:97]
	v_mul_f32_e32 v98, 0xbfb8aa3b, v90
	v_mul_f32_e32 v99, 0xbfb8aa3b, v91
	v_mul_f32_e32 v100, 0xbfb8aa3b, v92
	v_mul_f32_e32 v101, 0xbfb8aa3b, v93
	v_mul_f32_e32 v102, 0xbfb8aa3b, v94
	v_mul_f32_e32 v103, 0xbfb8aa3b, v95
	v_mul_f32_e32 v104, 0xbfb8aa3b, v96
	v_mul_f32_e32 v105, 0xbfb8aa3b, v97
	v_exp_f32_e32 v98, v98
	v_exp_f32_e32 v99, v99
	v_exp_f32_e32 v100, v100
	v_exp_f32_e32 v101, v101
	v_exp_f32_e32 v102, v102
	v_exp_f32_e32 v103, v103
	v_exp_f32_e32 v104, v104
	v_exp_f32_e32 v105, v105
	v_add_f32_e32 v98, 1.0, v98
	v_add_f32_e32 v99, 1.0, v99
	v_add_f32_e32 v100, 1.0, v100
	v_add_f32_e32 v101, 1.0, v101
	v_add_f32_e32 v102, 1.0, v102
	v_add_f32_e32 v103, 1.0, v103
	v_add_f32_e32 v104, 1.0, v104
	v_add_f32_e32 v105, 1.0, v105
	v_rcp_f32_e32 v98, v98
	v_rcp_f32_e32 v99, v99
	v_rcp_f32_e32 v100, v100
	v_rcp_f32_e32 v101, v101
	v_rcp_f32_e32 v102, v102
	v_rcp_f32_e32 v103, v103
	v_rcp_f32_e32 v104, v104
	v_rcp_f32_e32 v105, v105
	v_pk_mul_f32 v[90:91], v[90:91], v[98:99]
	v_pk_mul_f32 v[92:93], v[92:93], v[100:101]
	v_pk_mul_f32 v[94:95], v[94:95], v[102:103]
	v_pk_mul_f32 v[96:97], v[96:97], v[104:105]
	v_cvt_pk_bf16_f32 v90, v90, v91
	v_cvt_pk_bf16_f32 v91, v92, v93
	v_cvt_pk_bf16_f32 v92, v94, v95
	v_cvt_pk_bf16_f32 v93, v96, v97
	s_waitcnt lgkmcnt(1)
	v_mfma_f32_16x16x32_bf16 v[38:41], v[90:93], v[142:145], v[38:41]
	v_lshl_add_u64 v[0:1], v[74:75], 0, s[26:27]
	s_add_u32 s26, s26, 64
	v_add_co_u32_e32 v0, vcc, s31, v0
	s_waitcnt lgkmcnt(0)
	v_mfma_f32_16x16x32_bf16 v[38:41], v[50:53], v[146:149], v[38:41]
	s_addc_u32 s27, s27, 0
	v_add_u32_e32 v89, 64, v89
	v_add_u32_e32 v3, 64, v3
	v_add_u32_e32 v5, 0x80, v5
	v_addc_co_u32_e32 v1, vcc, 0, v1, vcc
	s_cmpk_eq_i32 s26, 0x100
	global_store_dwordx4 v[0:1], v[90:93], off sc1
	s_cbranch_scc0 .LBB0_1213
	ds_write_b128 v87, v[18:21] offset:53504
	ds_write_b128 v87, v[26:29] offset:55616
	ds_write_b128 v87, v[34:37] offset:57728
	ds_write_b128 v87, v[42:45] offset:59840
	s_and_saveexec_b64 s[0:1], s[6:7]
	ds_write_b128 v88, v[46:49] offset:53504
	s_or_b64 exec, exec, s[0:1]
	s_and_b64 vcc, exec, s[24:25]
	s_cbranch_vccz .LBB0_1228
	v_mov_b32_e32 v28, v2
	v_mov_b32_e32 v29, v2
	v_mov_b64_e32 v[20:21], v[28:29]
	v_mov_b64_e32 v[18:19], v[28:29]
	s_and_saveexec_b64 s[0:1], s[8:9]
	s_cbranch_execz .LBB0_1219
	global_load_dwordx4 v[18:21], v[64:65], off offset:768

; DEV float siluf_(float x) { return x * __builtin_amdgcn_rcpf(1.f + __expf(-x)); }
; #define LAS __attribute__((address_space(3)))
; DEV uint4 pack8(const float* f) { return make_uint4(pk2(f[0], f[1]), pk2(f[2], f[3]), pk2(f[4], f[5]), pk2(f[6], f[7])); }
; DEV void xc_gates_phase(LAS char* shm, const bf16_t* mi, bf16_t* xc, const bf16_t* WfT, const float* cw, const float* cb, float* gpart  ) {
;     ...
;             for (int ks = 0; ks < 4; ++ks) {
;                 const int cl = 32 * ks + 8 * fq, c = c0 + cl;
;                 float xv[8], t8[8];
;                 { const f32x4 b0 = *(const LAS f32x4*)(shm + CWL + 16384 + c * 4), b1 = *(const LAS f32x4*)(shm + CWL + 16384 + c * 4 + 16);
;                   xv[0] = b0[0]; xv[1] = b0[1]; xv[2] = b0[2]; xv[3] = b0[3]; xv[4] = b1[0]; xv[5] = b1[1]; xv[6] = b1[2]; xv[7] = b1[3]; }
;                 u32x4 raw3;
; #pragma unroll
;                 for (int tap = 0; tap < 4; ++tap) {
;                     const u32x4 rw = *(const LAS u32x4*)(stg + (fr + tap) * SRS_ + cl * 2);
;                     if (tap == 3) raw3 = rw;
;                     unpack8(make_uint4(rw[0], rw[1], rw[2], rw[3]), t8);
;                     const f32x4 w0 = *(const LAS f32x4*)(shm + CWL + tap * 4096 + c * 4), w1 = *(const LAS f32x4*)(shm + CWL + tap * 4096 + c * 4 + 16);
;                     xv[0] += t8[0] * w0[0]; xv[1] += t8[1] * w0[1]; xv[2] += t8[2] * w0[2]; xv[3] += t8[3] * w0[3];
;                     xv[4] += t8[4] * w1[0]; xv[5] += t8[5] * w1[1]; xv[6] += t8[6] * w1[2]; xv[7] += t8[7] * w1[3];
;                 }
; #pragma unroll
;                 for (int e = 0; e < 8; ++e) xv[e] = siluf_(xv[e]);
;                 const uint4 xp = pack8(xv);
;                 *(uint4*)(xc + (size_t)(m0 + fr) * DM + c) = xp;
;                 const u32x4 xpu = (u32x4){xp.x, xp.y, xp.z, xp.w};
;                 const bf16x8 bx = *(const LAS bf16x8*)(shm + (fr & 7) * WRS + c * 2);
;                 const bf16x8 bv = *(const LAS bf16x8*)(shm + WIMG + (fr & 7) * WRS + c * 2);
;                 acc = __builtin_amdgcn_mfma_f32_16x16x32_bf16(*(const bf16x8*)&xpu, bx, acc, 0, 0, 0);
;                 acc = __builtin_amdgcn_mfma_f32_16x16x32_bf16(*(const bf16x8*)&raw3, bv, acc, 0, 0, 0);
;             }
.LBB0_1229:
	ds_read_b128 v[90:93], v74 offset:16384
	ds_read_b128 v[94:97], v74 offset:16400
	ds_read_b128 v[98:101], v74
	ds_read_b128 v[102:105], v74 offset:16
	ds_read_b128 v[106:109], v75
	ds_read_b128 v[110:113], v75 offset:528
	ds_read_b128 v[114:117], v74 offset:4096
	ds_read_b128 v[118:121], v74 offset:4112
	ds_read_b128 v[122:125], v74 offset:8192
	ds_read_b128 v[126:129], v74 offset:8208
	ds_read_b128 v[130:133], v75 offset:1056
	ds_read_b128 v[50:53], v75 offset:1584
	ds_read_b128 v[134:137], v74 offset:12288
	ds_read_b128 v[138:141], v74 offset:12304
	s_waitcnt lgkmcnt(9)
	ds_read_b128 v[142:145], v3
	ds_read_b128 v[146:149], v3 offset:16512
	v_lshlrev_b32_e32 v150, 16, v106
	v_and_b32_e32 v151, 0xffff0000, v106
	v_lshlrev_b32_e32 v106, 16, v107
	v_and_b32_e32 v107, 0xffff0000, v107
	v_lshlrev_b32_e32 v160, 16, v108
	v_and_b32_e32 v161, 0xffff0000, v108
	v_lshlrev_b32_e32 v108, 16, v109
	v_and_b32_e32 v109, 0xffff0000, v109
	s_waitcnt lgkmcnt(10)
	v_lshlrev_b32_e32 v152, 16, v110
	v_and_b32_e32 v153, 0xffff0000, v110
	v_lshlrev_b32_e32 v110, 16, v111
	v_and_b32_e32 v111, 0xffff0000, v111
	v_lshlrev_b32_e32 v162, 16, v112
	v_and_b32_e32 v163, 0xffff0000, v112
	v_lshlrev_b32_e32 v112, 16, v113
	v_and_b32_e32 v113, 0xffff0000, v113
	v_pk_fma_f32 v[90:91], v[98:99], v[150:151], v[90:91]
	v_pk_fma_f32 v[92:93], v[100:101], v[106:107], v[92:93]
	v_pk_fma_f32 v[94:95], v[102:103], v[160:161], v[94:95]
	v_pk_fma_f32 v[96:97], v[104:105], v[108:109], v[96:97]
	s_waitcnt lgkmcnt(5)
	v_lshlrev_b32_e32 v154, 16, v130
	v_and_b32_e32 v155, 0xffff0000, v130
	v_lshlrev_b32_e32 v130, 16, v131
	v_and_b32_e32 v131, 0xffff0000, v131
	v_lshlrev_b32_e32 v164, 16, v132
	v_and_b32_e32 v165, 0xffff0000, v132
	v_lshlrev_b32_e32 v132, 16, v133
	v_and_b32_e32 v133, 0xffff0000, v133
	v_pk_fma_f32 v[90:91], v[114:115], v[152:153], v[90:91]
	v_pk_fma_f32 v[92:93], v[116:117], v[110:111], v[92:93]
	v_pk_fma_f32 v[94:95], v[118:119], v[162:163], v[94:95]
	v_pk_fma_f32 v[96:97], v[120:121], v[112:113], v[96:97]
	s_waitcnt lgkmcnt(4)
	v_lshlrev_b32_e32 v156, 16, v50
	v_and_b32_e32 v157, 0xffff0000, v50
	v_lshlrev_b32_e32 v158, 16, v51
	v_and_b32_e32 v159, 0xffff0000, v51
	v_lshlrev_b32_e32 v166, 16, v52
	v_and_b32_e32 v167, 0xffff0000, v52
	v_lshlrev_b32_e32 v168, 16, v53
	v_and_b32_e32 v169, 0xffff0000, v53
	v_pk_fma_f32 v[90:91], v[122:123], v[154:155], v[90:91]
	v_pk_fma_f32 v[92:93], v[124:125], v[130:131], v[92:93]
	v_pk_fma_f32 v[94:95], v[126:127], v[164:165], v[94:95]
	v_pk_fma_f32 v[96:97], v[128:129], v[132:133], v[96:97]
	s_waitcnt lgkmcnt(3)
	v_pk_fma_f32 v[90:91], v[134:135], v[156:157], v[90:91]
	v_pk_fma_f32 v[92:93], v[136:137], v[158:159], v[92:93]
	s_waitcnt lgkmcnt(2)
	v_pk_fma_f32 v[94:95], v[138:139], v[166:167], v[94:95]
	v_pk_fma_f32 v[96:97], v[140:141], v[168:169], v[96:97]
	v_mul_f32_e32 v89, 0xbfb8aa3b, v90
	v_mul_f32_e32 v98, 0xbfb8aa3b, v91
	v_mul_f32_e32 v99, 0xbfb8aa3b, v92
	v_mul_f32_e32 v100, 0xbfb8aa3b, v93
	v_mul_f32_e32 v101, 0xbfb8aa3b, v94
	v_mul_f32_e32 v102, 0xbfb8aa3b, v95
	v_mul_f32_e32 v103, 0xbfb8aa3b, v96
	v_mul_f32_e32 v104, 0xbfb8aa3b, v97
	v_exp_f32_e32 v89, v89
	v_exp_f32_e32 v98, v98
	v_exp_f32_e32 v99, v99
	v_exp_f32_e32 v100, v100
	v_exp_f32_e32 v101, v101
	v_exp_f32_e32 v102, v102
	v_exp_f32_e32 v103, v103
	v_exp_f32_e32 v104, v104
	v_add_f32_e32 v89, 1.0, v89
	v_add_f32_e32 v105, 1.0, v98
	v_add_f32_e32 v106, 1.0, v99
	v_add_f32_e32 v107, 1.0, v100
	v_add_f32_e32 v108, 1.0, v101
	v_add_f32_e32 v109, 1.0, v102
	v_add_f32_e32 v110, 1.0, v103
	v_add_f32_e32 v111, 1.0, v104
	v_rcp_f32_e32 v98, v89
	v_rcp_f32_e32 v99, v105
	v_rcp_f32_e32 v100, v106
	v_rcp_f32_e32 v101, v107
	v_rcp_f32_e32 v102, v108
	v_rcp_f32_e32 v103, v109
	v_rcp_f32_e32 v104, v110
	v_rcp_f32_e32 v105, v111
	v_pk_mul_f32 v[90:91], v[90:91], v[98:99]
	v_pk_mul_f32 v[92:93], v[92:93], v[100:101]
	v_pk_mul_f32 v[94:95], v[94:95], v[102:103]
	v_pk_mul_f32 v[96:97], v[96:97], v[104:105]
	v_cvt_pk_bf16_f32 v90, v90, v91
	v_cvt_pk_bf16_f32 v91, v92, v93
	v_cvt_pk_bf16_f32 v92, v94, v95
	v_cvt_pk_bf16_f32 v93, v96, v97
	s_waitcnt lgkmcnt(1)
	v_mfma_f32_16x16x32_bf16 v[38:41], v[90:93], v[142:145], v[38:41]
	v_lshl_add_u64 v[0:1], v[4:5], 0, s[24:25]
	s_add_u32 s24, s24, 64
	v_add_co_u32_e32 v0, vcc, s31, v0
	s_waitcnt lgkmcnt(0)
	v_mfma_f32_16x16x32_bf16 v[38:41], v[50:53], v[146:149], v[38:41]
	s_addc_u32 s25, s25, 0
	v_add_u32_e32 v75, 64, v75
	v_add_u32_e32 v3, 64, v3
	v_add_u32_e32 v74, 0x80, v74
	v_addc_co_u32_e32 v1, vcc, 0, v1, vcc
	s_cmpk_lg_i32 s24, 0x100
	global_store_dwordx4 v[0:1], v[90:93], off offset:256 sc1
	s_cbranch_scc1 .LBB0_1229
	s_movk_i32 s19, 0x100
	s_mov_b64 s[24:25], 0
	s_and_b64 vcc, exec, s[22:23]
	s_cbranch_vccz .LBB0_1198
	s_and_saveexec_b64 s[0:1], s[4:5]
	s_cbranch_execz .LBB0_1176
	s_ashr_i32 s19, s18, 31
	v_lshl_add_u64 v[0:1], s[18:19], 0, v[58:59]
	v_lshlrev_b64 v[0:1], 5, v[0:1]
	v_lshl_add_u64 v[0:1], v[54:55], 0, v[0:1]
	global_store_dword v[0:1], v38, off
	global_store_dword v[0:1], v39, off offset:32
	global_store_dword v[0:1], v40, off offset:64
	global_store_dword v[0:1], v41, off offset:96
	s_branch .LBB0_1176

; #define MLK_ISSUE(chunk_off_elems, buf) do { const char* kg_ = (const char*)(k + (chunk_off_elems)); _Pragma("unroll") for (int i_ = 0; i_ < 4; ++i_) \
;             __builtin_amdgcn_global_load_lds((const unsigned*)(kg_ + kvoff + (size_t)i_ * 16 * DM * 2), (LAS unsigned*)(shm + (buf) * 32768 + (i_ * 8 + wid) * 1024), 16, 0, 0); } while (0)
; template <int SKIP>
; DEV void mlstm_phase(LAS char* shm, const bf16_t* q, const bf16_t* k, const bf16_t* v, const float* gpart, const float* b_ig, const float* b_fg, bf16_t* hc, const bool pre) {
;     ...
;             if (j + 1 < SEQ / CHUNK) {
;                 const size_t cn = cb + (size_t)CHUNK * DM;
;                 MLK_ISSUE(cn, (j + 1) & 1);
; #pragma unroll
;                 for (int ks = 0; ks < 8; ++ks) qnx[ks] = *(const bf16x8*)(qfb + (size_t)(j + 1) * 16384 + ks * 512);
;                 if (wid < 4) vv = *(const uint4*)(v + cn + (size_t)(tid >> 2) * DM + vs * 32 + (tid & 3) * 8);
;             }
.LBB0_1501:
	s_waitcnt lgkmcnt(0)
	s_barrier
	s_and_b64 vcc, exec, s[70:71]
	s_cbranch_vccnz .Lpf1_done
	s_cmpk_eq_i32 s40, 0xff00
	s_cbranch_scc1 .Lpf1_skip
	v_lshl_add_u64 v[0:1], v[168:169], 0, s[64:65]
	s_mov_b64 s[0:1], 0x2032000
	v_lshl_add_u64 v[4:5], v[0:1], 0, s[0:1]
	s_add_i32 s0, s38, 0x8000
	s_and_b32 s0, s0, 0x8000
	s_add_i32 s29, s59, s0
	s_mov_b32 m0, s29
	s_mov_b64 s[0:1], 0x203a000
	global_load_lds_dwordx4 v[4:5], off
	v_lshl_add_u64 v[4:5], v[0:1], 0, s[0:1]
	s_add_i32 m0, s29, 0x2000
	s_mov_b64 s[0:1], 0x2042000
	global_load_lds_dwordx4 v[4:5], off
	v_lshl_add_u64 v[4:5], v[0:1], 0, s[0:1]
	s_add_i32 m0, s29, 0x4000
	s_mov_b64 s[0:1], 0x204a000
	global_load_lds_dwordx4 v[4:5], off
	v_lshl_add_u64 v[0:1], v[0:1], 0, s[0:1]
	s_add_i32 m0, s29, 0x6000
	global_load_lds_dwordx4 v[0:1], off
	s_add_u32 s0, s38, 0xc074000
	s_addc_u32 s1, s39, 0
	v_lshl_add_u64 v[4:5], v[170:171], 0, s[0:1]
	s_add_u32 s0, s0, 0x1000
	s_addc_u32 s1, s1, 0
	global_load_dwordx4 v[98:101], v[4:5], off
	global_load_dwordx4 v[90:93], v[4:5], off offset:1024
	global_load_dwordx4 v[82:85], v[4:5], off offset:2048
	global_load_dwordx4 v[78:81], v[4:5], off offset:3072
	v_lshl_add_u64 v[0:1], v[170:171], 0, s[0:1]
	global_load_dwordx4 v[106:109], v[0:1], off
	global_load_dwordx4 v[102:105], v[0:1], off offset:1024
	global_load_dwordx4 v[94:97], v[0:1], off offset:2048
	global_load_dwordx4 v[86:89], v[0:1], off offset:3072
	s_add_u32 s0, s64, 0xa07a000
	s_addc_u32 s1, s65, 0
	v_lshl_add_u64 v[0:1], v[174:175], 0, s[0:1]
	global_load_dwordx4 v[6:9], v[0:1], off
